# speedup vs baseline: 1.0022x; 1.0022x over previous
.LBB0_540:
	v_max_f32_e32 v80, v65, v65
	v_max_f32_e32 v81, v64, v64
	v_max_f32_e32 v80, v81, v80
	v_max3_f32 v80, v80, v66, v67
	v_max3_f32 v80, v80, v68, v69
	v_max3_f32 v80, v80, v70, v71
	v_max3_f32 v80, v80, v72, v73
	v_max3_f32 v80, v80, v74, v75
	v_max3_f32 v80, v80, v76, v77
	v_max3_f32 v80, v80, v78, v79
	v_mov_b32_e32 v81, v80
	s_nop 1
	v_permlane32_swap_b32_e32 v80, v81
	v_max_f32_e32 v81, v81, v81
	v_max_f32_e32 v80, v80, v80
	v_max_f32_e32 v187, v80, v81
	v_cmp_gt_u32_e64 s[4:5], 32, v163
	s_add_i32 s18, s6, 1
	.p2align	6

.LBB0_600:
	s_cmp_lt_i32 s7, 2
	s_cbranch_scc1 .LBB0_614
	s_nop 0
	v_max_f32_e32 v80, v65, v65
	v_max_f32_e32 v81, v64, v64
	v_max_f32_e32 v80, v81, v80
	v_max3_f32 v80, v80, v66, v67
	v_max3_f32 v80, v80, v68, v69
	v_max3_f32 v80, v80, v70, v71
	v_max3_f32 v80, v80, v72, v73
	v_max3_f32 v80, v80, v74, v75
	v_max3_f32 v80, v80, v76, v77
	v_max3_f32 v80, v80, v78, v79
	v_mov_b32_e32 v81, v80
	s_nop 1
	v_permlane32_swap_b32_e32 v80, v81
	v_max_f32_e32 v81, v81, v81
	v_max_f32_e32 v80, v80, v80
	v_max_f32_e32 v187, v80, v81
	.p2align	6

.LBB0_1349:
	v_add_f32_e32 v114, 0, v80
	v_add_f32_e32 v115, 0, v81
	v_add_f32_e32 v114, v82, v114
	v_add_f32_e32 v115, v83, v115
	v_add_f32_e32 v114, v84, v114
	v_add_f32_e32 v115, v85, v115
	v_add_f32_e32 v114, v86, v114
	v_add_f32_e32 v115, v87, v115
	v_add_f32_e32 v114, v88, v114
	v_add_f32_e32 v115, v89, v115
	v_add_f32_e32 v114, v90, v114
	v_add_f32_e32 v115, v91, v115
	v_add_f32_e32 v114, v92, v114
	v_add_f32_e32 v115, v93, v115
	v_add_f32_e32 v114, v94, v114
	v_add_f32_e32 v115, v95, v115
	s_waitcnt vmcnt(4) lgkmcnt(0)
	s_barrier
	v_add_f32_e32 v114, v114, v115
	v_max_f32_e32 v112, v112, v112
	v_max_f32_e32 v113, v113, v113
	v_add_f32_e32 v158, v158, v114
	v_max_f32_e32 v166, v112, v113
	s_cmp_lt_u32 s82, 2
	s_mov_b32 s84, 0
	s_cbranch_scc1 .LBB0_1367
	v_lshl_add_u32 v165, s82, 6, v162
	s_add_i32 s40, s82, -1
	.p2align	6

.LBB0_1370:
	s_cmp_eq_u32 s84, 0
	v_readfirstlane_b32 s45, v0
	v_readfirstlane_b32 s44, v0
	v_readfirstlane_b32 s75, v0
	v_readfirstlane_b32 s82, v0
	s_cbranch_scc1 .LBB0_1379
	v_add_f32_e32 v112, 0xc3200000, v161
	v_lshl_add_u32 v113, s84, 6, v163
	v_cmp_lt_f32_e32 vcc, v166, v112
	s_cmp_lg_u64 vcc, exec
	s_cbranch_scc1 .LBB0_1376
	.p2align	6

.LBB0_1436:
	s_cmp_lt_i32 s30, 2
	s_cbranch_scc1 .LBB0_1452
	v_max_f32_e32 v80, v65, v65
	v_max_f32_e32 v81, v64, v64
	v_max_f32_e32 v80, v81, v80
	v_max3_f32 v80, v80, v66, v67
	v_max3_f32 v80, v80, v68, v69
	v_max3_f32 v80, v80, v70, v71
	v_max3_f32 v80, v80, v72, v73
	v_max3_f32 v80, v80, v74, v75
	v_max3_f32 v80, v80, v76, v77
	v_max3_f32 v80, v80, v78, v79
	v_mov_b32_e32 v81, v80
	s_nop 1
	v_permlane32_swap_b32_e32 v80, v81
	v_max_f32_e32 v81, v81, v81
	v_max_f32_e32 v80, v80, v80
	v_max_f32_e32 v163, v80, v81
	.p2align	6
